# v13 plus GEMM K-loops: skip the first two counted DMA waits in the first K iteration of a unit (data already landed before the epilogue), compiler vmcnt(0) in the in-proj loop removed
# speedup vs baseline: 1.0204x; 1.0043x over previous
; #define PG8_STAGE(bufoff, gbase, voff) do { _Pragma("unroll") for (int _i = 0; _i < 2; ++_i) \
;         __builtin_amdgcn_global_load_lds((const unsigned*)((const char*)(gbase) + (voff)[_i]), (PG8_LAS unsigned*)(lds + (bufoff) + ldsw + _i * 8192), 16, 0, 0); } while (0)
; #define PG8_LDA(dst, b, h) do { _Pragma("unroll") for (int m = 0; m < 4; ++m) _Pragma("unroll") for (int k = 0; k < 2; ++k) dst[m][k] = *(const PG8_LAS bf16x8*)(lds + PG8_SA(b, h) + aoff + m * 2048 + k * 1024); } while (0)
; #define PG8_LDB(dst, b, h) do { _Pragma("unroll") for (int n = 0; n < 2; ++n) _Pragma("unroll") for (int k = 0; k < 2; ++k) dst[n][k] = *(const PG8_LAS bf16x8*)(lds + PG8_SB(b, h) + boff + n * 2048 + k * 1024); } while (0)
; #define PG8_MMA(ai, bj, At, Bt) do { __builtin_amdgcn_s_setprio(1); _Pragma("unroll") for (int m = 0; m < 4; ++m) _Pragma("unroll") for (int n = 0; n < 2; ++n) _Pragma("unroll") for (int k = 0; k < 2; ++k) \
;         acc[ai][bj][m][n] = __builtin_amdgcn_mfma_f32_16x16x32_bf16(Bt[n][k], At[m][k], acc[ai][bj][m][n], 0, 0, 0); __builtin_amdgcn_s_setprio(0); } while (0)
; #define PG8_WAIT_V(n) asm volatile("s_waitcnt vmcnt(" #n ")" ::: "memory")
; #define PG8_WAIT_L(n) asm volatile("s_waitcnt lgkmcnt(" #n ")" ::: "memory")
; #define PG8_BAR __builtin_amdgcn_s_barrier()
; #define PG8_SCHED __builtin_amdgcn_sched_barrier(0)
; template <class Epi, class Sched, bool ALIGN_EPI = false, bool SP2 = false>
; __device__ __forceinline__ void gemm_phase(PG8_LAS unsigned char* lds, const Gemm g, const Sched& S, const Epi& E) {
;     ...
;             PG8_LDB(B0, 0, 0); PG8_LDB(B1, 0, 1); PG8_SCHED; PG8_LDA(At, 0, 0); PG8_STAGE(PG8_SA(1, 1), a1 + hstep, voffA);
;             PG8_WAIT_V(8); PG8_WAIT_L(0); PG8_BAR; PG8_MMA(0, 0, At, B0); PG8_MMA(0, 1, At, B1); PG8_BAR; PG8_SCHED;
;             PG8_LDA(At, 0, 1); PG8_STAGE(PG8_SB(0, 0), b2, voffB); PG8_STAGE(PG8_SB(0, 1), b2 + hstep, voffB); PG8_STAGE(PG8_SA(0, 0), a2, voffA);
.LBB0_411:
	ds_read_b128 v[130:133], v218
	ds_read_b128 v[134:137], v218 offset:1024
	ds_read_b128 v[138:141], v218 offset:2048
	ds_read_b128 v[142:145], v218 offset:3072
	ds_read_b128 v[146:149], v219
	ds_read_b128 v[150:153], v219 offset:1024
	ds_read_b128 v[154:157], v219 offset:2048
	ds_read_b128 v[158:161], v219 offset:3072
	s_add_u32 s6, s4, 0xfffc0080
	s_addc_u32 s7, s5, -1
	s_cmp_eq_u32 s37, 12
	s_cselect_b32 s45, s0, s7
	s_cselect_b32 s44, s1, s6
	s_cselect_b32 s7, s9, s35
	s_cselect_b32 s6, s12, s33
	v_lshl_add_u64 v[226:227], s[4:5], 0, v[188:189]
	s_add_i32 m0, s51, 0xc000
	ds_read_b128 v[162:165], v220
	ds_read_b128 v[166:169], v220 offset:1024
	ds_read_b128 v[170:173], v220 offset:2048
	ds_read_b128 v[196:199], v220 offset:3072
	ds_read_b128 v[200:203], v220 offset:4096
	ds_read_b128 v[204:207], v220 offset:5120
	ds_read_b128 v[208:211], v220 offset:6144
	ds_read_b128 v[212:215], v220 offset:7168
	global_load_lds_dwordx4 v[226:227], off
	v_lshl_add_u64 v[226:227], s[4:5], 0, v[190:191]
	s_add_i32 m0, s51, 0xe000
	s_nop 0
	global_load_lds_dwordx4 v[226:227], off
	s_cmp_eq_u32 s37, -2
	s_cbranch_scc1 .Lks_p1_0
	s_waitcnt vmcnt(8)
.Lks_p1_0:
	s_waitcnt lgkmcnt(0)
	s_barrier
	s_setprio 1
	s_waitcnt lgkmcnt(0)
	v_mfma_f32_16x16x32_bf16 v[126:129], v[130:133], v[162:165], v[126:129]
	v_mfma_f32_16x16x32_bf16 v[122:125], v[138:141], v[162:165], v[122:125]
	v_mfma_f32_16x16x32_bf16 v[110:113], v[130:133], v[170:173], v[110:113]
	v_mfma_f32_16x16x32_bf16 v[106:109], v[138:141], v[170:173], v[106:109]
	v_mfma_f32_16x16x32_bf16 v[94:97], v[130:133], v[200:203], v[94:97]
	v_mfma_f32_16x16x32_bf16 v[90:93], v[138:141], v[200:203], v[90:93]
	v_mfma_f32_16x16x32_bf16 v[78:81], v[130:133], v[208:211], v[78:81]
	v_mfma_f32_16x16x32_bf16 v[74:77], v[138:141], v[208:211], v[74:77]
	v_mfma_f32_16x16x32_bf16 v[126:129], v[134:137], v[166:169], v[126:129]
	v_mfma_f32_16x16x32_bf16 v[122:125], v[142:145], v[166:169], v[122:125]
	v_mfma_f32_16x16x32_bf16 v[110:113], v[134:137], v[196:199], v[110:113]
	v_mfma_f32_16x16x32_bf16 v[106:109], v[142:145], v[196:199], v[106:109]
	v_mfma_f32_16x16x32_bf16 v[94:97], v[134:137], v[204:207], v[94:97]
	v_mfma_f32_16x16x32_bf16 v[90:93], v[142:145], v[204:207], v[90:93]
	v_mfma_f32_16x16x32_bf16 v[78:81], v[134:137], v[212:215], v[78:81]
	v_mfma_f32_16x16x32_bf16 v[74:77], v[142:145], v[212:215], v[74:77]
	s_setprio 0
	s_setprio 1
	v_mfma_f32_16x16x32_bf16 v[118:121], v[146:149], v[162:165], v[118:121]
	v_mfma_f32_16x16x32_bf16 v[114:117], v[154:157], v[162:165], v[114:117]
	v_mfma_f32_16x16x32_bf16 v[102:105], v[146:149], v[170:173], v[102:105]
	v_mfma_f32_16x16x32_bf16 v[98:101], v[154:157], v[170:173], v[98:101]
	v_mfma_f32_16x16x32_bf16 v[86:89], v[146:149], v[200:203], v[86:89]
	v_mfma_f32_16x16x32_bf16 v[82:85], v[154:157], v[200:203], v[82:85]
	v_mfma_f32_16x16x32_bf16 v[70:73], v[146:149], v[208:211], v[70:73]
	v_mfma_f32_16x16x32_bf16 v[66:69], v[154:157], v[208:211], v[66:69]
	v_mfma_f32_16x16x32_bf16 v[118:121], v[150:153], v[166:169], v[118:121]
	v_mfma_f32_16x16x32_bf16 v[114:117], v[158:161], v[166:169], v[114:117]
	v_mfma_f32_16x16x32_bf16 v[102:105], v[150:153], v[196:199], v[102:105]
	v_mfma_f32_16x16x32_bf16 v[98:101], v[158:161], v[196:199], v[98:101]
	v_mfma_f32_16x16x32_bf16 v[86:89], v[150:153], v[204:207], v[86:89]
	v_mfma_f32_16x16x32_bf16 v[82:85], v[158:161], v[204:207], v[82:85]
	v_mfma_f32_16x16x32_bf16 v[70:73], v[150:153], v[212:215], v[70:73]
	v_mfma_f32_16x16x32_bf16 v[66:69], v[158:161], v[212:215], v[66:69]
	s_setprio 0
	s_barrier
	s_add_i32 s43, s86, s50
	v_lshl_add_u64 v[226:227], s[6:7], 0, v[178:179]
	s_mov_b32 m0, s43
	ds_read_b128 v[162:165], v220 offset:16384
	ds_read_b128 v[166:169], v220 offset:17408
	ds_read_b128 v[170:173], v220 offset:18432
	ds_read_b128 v[196:199], v220 offset:19456
	ds_read_b128 v[200:203], v220 offset:20480
	ds_read_b128 v[204:207], v220 offset:21504
	ds_read_b128 v[208:211], v220 offset:22528
	ds_read_b128 v[212:215], v220 offset:23552
	global_load_lds_dwordx4 v[226:227], off
	s_add_i32 m0, s43, 0x2000
	s_add_u32 s46, s6, 0x40000
	v_lshl_add_u64 v[228:229], s[6:7], 0, v[182:183]
	s_addc_u32 s47, s7, 0
	s_add_i32 s43, s87, s50
	global_load_lds_dwordx4 v[228:229], off
	v_lshl_add_u64 v[230:231], s[46:47], 0, v[178:179]
	s_mov_b32 m0, s43
	v_lshl_add_u64 v[232:233], s[44:45], 0, v[180:181]
	global_load_lds_dwordx4 v[230:231], off
	v_lshl_add_u64 v[230:231], s[46:47], 0, v[182:183]
	s_add_i32 m0, s43, 0x2000
	s_nop 0
	global_load_lds_dwordx4 v[230:231], off
	v_lshl_add_u64 v[230:231], s[44:45], 0, v[176:177]
	s_mov_b32 m0, s51
	s_nop 0
	global_load_lds_dwordx4 v[230:231], off
	s_mov_b32 m0, s52
	s_nop 0
	global_load_lds_dwordx4 v[232:233], off
	s_cmp_eq_u32 s37, -2
	s_cbranch_scc1 .Lks_p1_1
	s_waitcnt vmcnt(8)
; #define PG8_STAGE(bufoff, gbase, voff) do { _Pragma("unroll") for (int _i = 0; _i < 2; ++_i) \
;         __builtin_amdgcn_global_load_lds((const unsigned*)((const char*)(gbase) + (voff)[_i]), (PG8_LAS unsigned*)(lds + (bufoff) + ldsw + _i * 8192), 16, 0, 0); } while (0)
; #define PG8_LDA(dst, b, h) do { _Pragma("unroll") for (int m = 0; m < 4; ++m) _Pragma("unroll") for (int k = 0; k < 2; ++k) dst[m][k] = *(const PG8_LAS bf16x8*)(lds + PG8_SA(b, h) + aoff + m * 2048 + k * 1024); } while (0)
; #define PG8_LDB(dst, b, h) do { _Pragma("unroll") for (int n = 0; n < 2; ++n) _Pragma("unroll") for (int k = 0; k < 2; ++k) dst[n][k] = *(const PG8_LAS bf16x8*)(lds + PG8_SB(b, h) + boff + n * 2048 + k * 1024); } while (0)
; #define PG8_MMA(ai, bj, At, Bt) do { __builtin_amdgcn_s_setprio(1); _Pragma("unroll") for (int m = 0; m < 4; ++m) _Pragma("unroll") for (int n = 0; n < 2; ++n) _Pragma("unroll") for (int k = 0; k < 2; ++k) \
;         acc[ai][bj][m][n] = __builtin_amdgcn_mfma_f32_16x16x32_bf16(Bt[n][k], At[m][k], acc[ai][bj][m][n], 0, 0, 0); __builtin_amdgcn_s_setprio(0); } while (0)
; #define PG8_WAIT_V(n) asm volatile("s_waitcnt vmcnt(" #n ")" ::: "memory")
; #define PG8_WAIT_L(n) asm volatile("s_waitcnt lgkmcnt(" #n ")" ::: "memory")
; #define PG8_BAR __builtin_amdgcn_s_barrier()
; #define PG8_SCHED __builtin_amdgcn_sched_barrier(0)
; template <class Epi, class Sched, bool ALIGN_EPI = false, bool SP2 = false>
; __device__ __forceinline__ void gemm_phase(PG8_LAS unsigned char* lds, const Gemm g, const Sched& S, const Epi& E) {
;     ...
;             PG8_WAIT_V(8); PG8_WAIT_L(0); PG8_BAR; PG8_MMA(1, 0, At, B0); PG8_MMA(1, 1, At, B1); PG8_BAR; PG8_SCHED;
;             PG8_LDB(B0, 1, 0); PG8_LDB(B1, 1, 1); PG8_SCHED; PG8_LDA(At, 1, 0); PG8_STAGE(PG8_SA(0, 1), a2 + hstep, voffA);
;             PG8_WAIT_V(8); PG8_WAIT_L(0); PG8_BAR; PG8_MMA(0, 0, At, B0); PG8_MMA(0, 1, At, B1); PG8_BAR; PG8_SCHED;
.Lks_p1_1:
	s_waitcnt lgkmcnt(0)
	s_barrier
	s_setprio 1
	s_waitcnt lgkmcnt(0)
	v_mfma_f32_16x16x32_bf16 v[62:65], v[130:133], v[162:165], v[62:65]
	v_mfma_f32_16x16x32_bf16 v[58:61], v[138:141], v[162:165], v[58:61]
	v_mfma_f32_16x16x32_bf16 v[46:49], v[130:133], v[170:173], v[46:49]
	v_mfma_f32_16x16x32_bf16 v[42:45], v[138:141], v[170:173], v[42:45]
	v_mfma_f32_16x16x32_bf16 v[30:33], v[130:133], v[200:203], v[30:33]
	v_mfma_f32_16x16x32_bf16 v[26:29], v[138:141], v[200:203], v[26:29]
	v_mfma_f32_16x16x32_bf16 v[14:17], v[130:133], v[208:211], v[14:17]
	v_mfma_f32_16x16x32_bf16 v[10:13], v[138:141], v[208:211], v[10:13]
	v_mfma_f32_16x16x32_bf16 v[62:65], v[134:137], v[166:169], v[62:65]
	v_mfma_f32_16x16x32_bf16 v[58:61], v[142:145], v[166:169], v[58:61]
	v_mfma_f32_16x16x32_bf16 v[46:49], v[134:137], v[196:199], v[46:49]
	v_mfma_f32_16x16x32_bf16 v[42:45], v[142:145], v[196:199], v[42:45]
	v_mfma_f32_16x16x32_bf16 v[30:33], v[134:137], v[204:207], v[30:33]
	v_mfma_f32_16x16x32_bf16 v[26:29], v[142:145], v[204:207], v[26:29]
	v_mfma_f32_16x16x32_bf16 v[14:17], v[134:137], v[212:215], v[14:17]
	v_mfma_f32_16x16x32_bf16 v[10:13], v[142:145], v[212:215], v[10:13]
	s_setprio 0
	s_setprio 1
	v_mfma_f32_16x16x32_bf16 v[54:57], v[146:149], v[162:165], v[54:57]
	v_mfma_f32_16x16x32_bf16 v[50:53], v[154:157], v[162:165], v[50:53]
	v_mfma_f32_16x16x32_bf16 v[38:41], v[146:149], v[170:173], v[38:41]
	v_mfma_f32_16x16x32_bf16 v[34:37], v[154:157], v[170:173], v[34:37]
	v_mfma_f32_16x16x32_bf16 v[22:25], v[146:149], v[200:203], v[22:25]
	v_mfma_f32_16x16x32_bf16 v[18:21], v[154:157], v[200:203], v[18:21]
	v_mfma_f32_16x16x32_bf16 v[6:9], v[146:149], v[208:211], v[6:9]
	v_mfma_f32_16x16x32_bf16 v[2:5], v[154:157], v[208:211], v[2:5]
	v_mfma_f32_16x16x32_bf16 v[54:57], v[150:153], v[166:169], v[54:57]
	v_mfma_f32_16x16x32_bf16 v[50:53], v[158:161], v[166:169], v[50:53]
	v_mfma_f32_16x16x32_bf16 v[38:41], v[150:153], v[196:199], v[38:41]
	v_mfma_f32_16x16x32_bf16 v[34:37], v[158:161], v[196:199], v[34:37]
	v_mfma_f32_16x16x32_bf16 v[22:25], v[150:153], v[204:207], v[22:25]
	v_mfma_f32_16x16x32_bf16 v[18:21], v[158:161], v[204:207], v[18:21]
	v_mfma_f32_16x16x32_bf16 v[6:9], v[150:153], v[212:215], v[6:9]
	v_mfma_f32_16x16x32_bf16 v[2:5], v[158:161], v[212:215], v[2:5]
	s_setprio 0
	s_barrier
	s_add_i32 s43, 0, 0x18000
	s_add_i32 s46, 0, 0x1c000
	v_add_u32_e32 v142, s43, v217
	v_add_u32_e32 v158, s46, v217
	ds_read_b128 v[130:133], v142
	ds_read_b128 v[134:137], v142 offset:1024
	ds_read_b128 v[138:141], v142 offset:2048
	ds_read_b128 v[142:145], v142 offset:3072
	ds_read_b128 v[146:149], v158
	ds_read_b128 v[150:153], v158 offset:1024
	ds_read_b128 v[154:157], v158 offset:2048
	ds_read_b128 v[158:161], v158 offset:3072
	s_add_u32 s44, s44, 0x40000
	s_addc_u32 s45, s45, 0
	s_mov_b32 m0, s53
	v_lshl_add_u64 v[234:235], s[44:45], 0, v[176:177]
	ds_read_b128 v[162:165], v220 offset:32768
	ds_read_b128 v[166:169], v220 offset:33792
	ds_read_b128 v[170:173], v220 offset:34816
	ds_read_b128 v[196:199], v220 offset:35840
	ds_read_b128 v[200:203], v220 offset:36864
	ds_read_b128 v[204:207], v220 offset:37888
	ds_read_b128 v[208:211], v220 offset:38912
	ds_read_b128 v[212:215], v220 offset:39936
	global_load_lds_dwordx4 v[234:235], off
	v_lshl_add_u64 v[234:235], s[44:45], 0, v[180:181]
	s_mov_b32 m0, s54
	s_nop 0
	global_load_lds_dwordx4 v[234:235], off
	s_waitcnt vmcnt(8)
	s_waitcnt lgkmcnt(0)
	s_barrier
	s_setprio 1
	s_waitcnt lgkmcnt(0)
	v_mfma_f32_16x16x32_bf16 v[126:129], v[130:133], v[162:165], v[126:129]
	v_mfma_f32_16x16x32_bf16 v[122:125], v[138:141], v[162:165], v[122:125]
	v_mfma_f32_16x16x32_bf16 v[110:113], v[130:133], v[170:173], v[110:113]
	v_mfma_f32_16x16x32_bf16 v[106:109], v[138:141], v[170:173], v[106:109]
	v_mfma_f32_16x16x32_bf16 v[94:97], v[130:133], v[200:203], v[94:97]
	v_mfma_f32_16x16x32_bf16 v[90:93], v[138:141], v[200:203], v[90:93]
	v_mfma_f32_16x16x32_bf16 v[78:81], v[130:133], v[208:211], v[78:81]
	v_mfma_f32_16x16x32_bf16 v[74:77], v[138:141], v[208:211], v[74:77]
	v_mfma_f32_16x16x32_bf16 v[126:129], v[134:137], v[166:169], v[126:129]
	v_mfma_f32_16x16x32_bf16 v[122:125], v[142:145], v[166:169], v[122:125]
	v_mfma_f32_16x16x32_bf16 v[110:113], v[134:137], v[196:199], v[110:113]
	v_mfma_f32_16x16x32_bf16 v[106:109], v[142:145], v[196:199], v[106:109]
	v_mfma_f32_16x16x32_bf16 v[94:97], v[134:137], v[204:207], v[94:97]
	v_mfma_f32_16x16x32_bf16 v[90:93], v[142:145], v[204:207], v[90:93]
	v_mfma_f32_16x16x32_bf16 v[78:81], v[134:137], v[212:215], v[78:81]
	v_mfma_f32_16x16x32_bf16 v[74:77], v[142:145], v[212:215], v[74:77]
	s_setprio 0
	s_setprio 1
	v_mfma_f32_16x16x32_bf16 v[118:121], v[146:149], v[162:165], v[118:121]
	v_mfma_f32_16x16x32_bf16 v[114:117], v[154:157], v[162:165], v[114:117]
	v_mfma_f32_16x16x32_bf16 v[102:105], v[146:149], v[170:173], v[102:105]
	v_mfma_f32_16x16x32_bf16 v[98:101], v[154:157], v[170:173], v[98:101]
	v_mfma_f32_16x16x32_bf16 v[86:89], v[146:149], v[200:203], v[86:89]
	v_mfma_f32_16x16x32_bf16 v[82:85], v[154:157], v[200:203], v[82:85]
	v_mfma_f32_16x16x32_bf16 v[70:73], v[146:149], v[208:211], v[70:73]
	v_mfma_f32_16x16x32_bf16 v[66:69], v[154:157], v[208:211], v[66:69]
	v_mfma_f32_16x16x32_bf16 v[118:121], v[150:153], v[166:169], v[118:121]
	v_mfma_f32_16x16x32_bf16 v[114:117], v[158:161], v[166:169], v[114:117]
	v_mfma_f32_16x16x32_bf16 v[102:105], v[150:153], v[196:199], v[102:105]
	v_mfma_f32_16x16x32_bf16 v[98:101], v[158:161], v[196:199], v[98:101]
	v_mfma_f32_16x16x32_bf16 v[86:89], v[150:153], v[204:207], v[86:89]
	v_mfma_f32_16x16x32_bf16 v[82:85], v[158:161], v[204:207], v[82:85]
	v_mfma_f32_16x16x32_bf16 v[70:73], v[150:153], v[212:215], v[70:73]
	v_mfma_f32_16x16x32_bf16 v[66:69], v[158:161], v[212:215], v[66:69]
	s_setprio 0
	s_barrier
; #define PG8_STAGE(bufoff, gbase, voff) do { _Pragma("unroll") for (int _i = 0; _i < 2; ++_i) \
;         __builtin_amdgcn_global_load_lds((const unsigned*)((const char*)(gbase) + (voff)[_i]), (PG8_LAS unsigned*)(lds + (bufoff) + ldsw + _i * 8192), 16, 0, 0); } while (0)
; #define PG8_LDA(dst, b, h) do { _Pragma("unroll") for (int m = 0; m < 4; ++m) _Pragma("unroll") for (int k = 0; k < 2; ++k) dst[m][k] = *(const PG8_LAS bf16x8*)(lds + PG8_SA(b, h) + aoff + m * 2048 + k * 1024); } while (0)
; #define PG8_MMA(ai, bj, At, Bt) do { __builtin_amdgcn_s_setprio(1); _Pragma("unroll") for (int m = 0; m < 4; ++m) _Pragma("unroll") for (int n = 0; n < 2; ++n) _Pragma("unroll") for (int k = 0; k < 2; ++k) \
;         acc[ai][bj][m][n] = __builtin_amdgcn_mfma_f32_16x16x32_bf16(Bt[n][k], At[m][k], acc[ai][bj][m][n], 0, 0, 0); __builtin_amdgcn_s_setprio(0); } while (0)
; #define PG8_WAIT_V(n) asm volatile("s_waitcnt vmcnt(" #n ")" ::: "memory")
; #define PG8_WAIT_L(n) asm volatile("s_waitcnt lgkmcnt(" #n ")" ::: "memory")
; #define PG8_BAR __builtin_amdgcn_s_barrier()
; #define PG8_SCHED __builtin_amdgcn_sched_barrier(0)
; template <class Epi, class Sched, bool ALIGN_EPI = false, bool SP2 = false>
; __device__ __forceinline__ void gemm_phase(PG8_LAS unsigned char* lds, const Gemm g, const Sched& S, const Epi& E) {
;     ...
;         for (int t = 0; t < nt; t += 2) {
;     ...
;             PG8_LDA(At, 1, 1); PG8_STAGE(PG8_SB(1, 0), b3, voffB); PG8_STAGE(PG8_SB(1, 1), b3 + hstep, voffB); PG8_STAGE(PG8_SA(1, 0), a3, voffA);
;             PG8_WAIT_V(8); PG8_WAIT_L(0); PG8_BAR; PG8_MMA(1, 0, At, B0); PG8_MMA(1, 1, At, B1); PG8_BAR; PG8_SCHED;
	s_add_i32 s43, s43, s50
	v_lshl_add_u64 v[226:227], v[226:227], 0, s[20:21]
	s_mov_b32 m0, s43
	ds_read_b128 v[162:165], v220 offset:49152
	ds_read_b128 v[166:169], v220 offset:50176
	ds_read_b128 v[170:173], v220 offset:51200
	ds_read_b128 v[196:199], v220 offset:52224
	ds_read_b128 v[200:203], v220 offset:53248
	ds_read_b128 v[204:207], v220 offset:54272
	ds_read_b128 v[208:211], v220 offset:55296
	ds_read_b128 v[212:215], v220 offset:56320
	global_load_lds_dwordx4 v[226:227], off
	s_add_i32 m0, s43, 0x2000
	s_add_u32 s6, s6, 0x40080
	v_lshl_add_u64 v[226:227], v[228:229], 0, s[20:21]
	s_addc_u32 s7, s7, 0
	s_add_i32 s43, s46, s50
	global_load_lds_dwordx4 v[226:227], off
	v_lshl_add_u64 v[226:227], s[6:7], 0, v[178:179]
	s_mov_b32 m0, s43
	s_nop 0
	global_load_lds_dwordx4 v[226:227], off
	v_lshl_add_u64 v[226:227], s[6:7], 0, v[182:183]
	s_add_i32 m0, s43, 0x2000
	s_nop 0
	global_load_lds_dwordx4 v[226:227], off
	v_lshl_add_u64 v[226:227], v[230:231], 0, s[20:21]
	s_mov_b32 m0, s67
	s_nop 0
	global_load_lds_dwordx4 v[226:227], off
	v_lshl_add_u64 v[226:227], v[232:233], 0, s[20:21]
	s_mov_b32 m0, s68
	s_nop 0
	global_load_lds_dwordx4 v[226:227], off
	s_waitcnt vmcnt(8)
	s_waitcnt lgkmcnt(0)
	s_barrier
	s_setprio 1
	s_waitcnt lgkmcnt(0)
	v_mfma_f32_16x16x32_bf16 v[62:65], v[130:133], v[162:165], v[62:65]
	v_mfma_f32_16x16x32_bf16 v[58:61], v[138:141], v[162:165], v[58:61]
	v_mfma_f32_16x16x32_bf16 v[46:49], v[130:133], v[170:173], v[46:49]
	v_mfma_f32_16x16x32_bf16 v[42:45], v[138:141], v[170:173], v[42:45]
	v_mfma_f32_16x16x32_bf16 v[30:33], v[130:133], v[200:203], v[30:33]
	v_mfma_f32_16x16x32_bf16 v[26:29], v[138:141], v[200:203], v[26:29]
	v_mfma_f32_16x16x32_bf16 v[14:17], v[130:133], v[208:211], v[14:17]
	v_mfma_f32_16x16x32_bf16 v[10:13], v[138:141], v[208:211], v[10:13]
	v_mfma_f32_16x16x32_bf16 v[62:65], v[134:137], v[166:169], v[62:65]
	v_mfma_f32_16x16x32_bf16 v[58:61], v[142:145], v[166:169], v[58:61]
	v_mfma_f32_16x16x32_bf16 v[46:49], v[134:137], v[196:199], v[46:49]
	v_mfma_f32_16x16x32_bf16 v[42:45], v[142:145], v[196:199], v[42:45]
	v_mfma_f32_16x16x32_bf16 v[30:33], v[134:137], v[204:207], v[30:33]
	v_mfma_f32_16x16x32_bf16 v[26:29], v[142:145], v[204:207], v[26:29]
	v_mfma_f32_16x16x32_bf16 v[14:17], v[134:137], v[212:215], v[14:17]
	v_mfma_f32_16x16x32_bf16 v[10:13], v[142:145], v[212:215], v[10:13]
	s_setprio 0
	s_setprio 1
	v_mfma_f32_16x16x32_bf16 v[54:57], v[146:149], v[162:165], v[54:57]
	v_mfma_f32_16x16x32_bf16 v[50:53], v[154:157], v[162:165], v[50:53]
	v_mfma_f32_16x16x32_bf16 v[38:41], v[146:149], v[170:173], v[38:41]
	v_mfma_f32_16x16x32_bf16 v[34:37], v[154:157], v[170:173], v[34:37]
	v_mfma_f32_16x16x32_bf16 v[22:25], v[146:149], v[200:203], v[22:25]
	v_mfma_f32_16x16x32_bf16 v[18:21], v[154:157], v[200:203], v[18:21]
	v_mfma_f32_16x16x32_bf16 v[6:9], v[146:149], v[208:211], v[6:9]
	v_mfma_f32_16x16x32_bf16 v[2:5], v[154:157], v[208:211], v[2:5]
	v_mfma_f32_16x16x32_bf16 v[54:57], v[150:153], v[166:169], v[54:57]
	v_mfma_f32_16x16x32_bf16 v[50:53], v[158:161], v[166:169], v[50:53]
	v_mfma_f32_16x16x32_bf16 v[38:41], v[150:153], v[196:199], v[38:41]
	v_mfma_f32_16x16x32_bf16 v[34:37], v[158:161], v[196:199], v[34:37]
	v_mfma_f32_16x16x32_bf16 v[22:25], v[150:153], v[204:207], v[22:25]
	v_mfma_f32_16x16x32_bf16 v[18:21], v[158:161], v[204:207], v[18:21]
	v_mfma_f32_16x16x32_bf16 v[6:9], v[150:153], v[212:215], v[6:9]
	v_mfma_f32_16x16x32_bf16 v[2:5], v[158:161], v[212:215], v[2:5]
	s_setprio 0
	s_barrier
	s_add_i32 s37, s37, 2
	s_add_u32 s4, s4, 0x100
	s_addc_u32 s5, s5, 0
	s_add_u32 s33, s33, 0x100
	s_addc_u32 s35, s35, 0
	s_cmp_gt_u32 s37, 13
	s_cbranch_scc0 .LBB0_411
	s_and_b64 vcc, exec, s[22:23]
	s_cbranch_vccz .LBB0_414
	s_barrier

; #define PG8_STAGE(bufoff, gbase, voff) do { _Pragma("unroll") for (int _i = 0; _i < 2; ++_i) \
;         __builtin_amdgcn_global_load_lds((const unsigned*)((const char*)(gbase) + (voff)[_i]), (PG8_LAS unsigned*)(lds + (bufoff) + ldsw + _i * 8192), 16, 0, 0); } while (0)
; #define PG8_LDA(dst, b, h) do { _Pragma("unroll") for (int m = 0; m < 4; ++m) _Pragma("unroll") for (int k = 0; k < 2; ++k) dst[m][k] = *(const PG8_LAS bf16x8*)(lds + PG8_SA(b, h) + aoff + m * 2048 + k * 1024); } while (0)
; #define PG8_LDB(dst, b, h) do { _Pragma("unroll") for (int n = 0; n < 2; ++n) _Pragma("unroll") for (int k = 0; k < 2; ++k) dst[n][k] = *(const PG8_LAS bf16x8*)(lds + PG8_SB(b, h) + boff + n * 2048 + k * 1024); } while (0)
; #define PG8_MMA(ai, bj, At, Bt) do { __builtin_amdgcn_s_setprio(1); _Pragma("unroll") for (int m = 0; m < 4; ++m) _Pragma("unroll") for (int n = 0; n < 2; ++n) _Pragma("unroll") for (int k = 0; k < 2; ++k) \
;         acc[ai][bj][m][n] = __builtin_amdgcn_mfma_f32_16x16x32_bf16(Bt[n][k], At[m][k], acc[ai][bj][m][n], 0, 0, 0); __builtin_amdgcn_s_setprio(0); } while (0)
; #define PG8_WAIT_V(n) asm volatile("s_waitcnt vmcnt(" #n ")" ::: "memory")
; #define PG8_WAIT_L(n) asm volatile("s_waitcnt lgkmcnt(" #n ")" ::: "memory")
; #define PG8_BAR __builtin_amdgcn_s_barrier()
; #define PG8_SCHED __builtin_amdgcn_sched_barrier(0)
; template <class Epi, class Sched, bool ALIGN_EPI = false, bool SP2 = false>
; __device__ __forceinline__ void gemm_phase(PG8_LAS unsigned char* lds, const Gemm g, const Sched& S, const Epi& E) {
;     ...
;             PG8_LDB(B0, 0, 0); PG8_LDB(B1, 0, 1); PG8_SCHED; PG8_LDA(At, 0, 0); PG8_STAGE(PG8_SA(1, 1), a1 + hstep, voffA);
;             PG8_WAIT_V(8); PG8_WAIT_L(0); PG8_BAR; PG8_MMA(0, 0, At, B0); PG8_MMA(0, 1, At, B1); PG8_BAR; PG8_SCHED;
;             PG8_LDA(At, 0, 1); PG8_STAGE(PG8_SB(0, 0), b2, voffB); PG8_STAGE(PG8_SB(0, 1), b2 + hstep, voffB); PG8_STAGE(PG8_SA(0, 0), a2, voffA);
.LBB0_1236:
	ds_read_b128 v[128:131], v175
	ds_read_b128 v[132:135], v175 offset:1024
	ds_read_b128 v[136:139], v175 offset:2048
	ds_read_b128 v[140:143], v175 offset:3072
	ds_read_b128 v[144:147], v176
	ds_read_b128 v[148:151], v176 offset:1024
	ds_read_b128 v[164:167], v176 offset:2048
	ds_read_b128 v[168:171], v176 offset:3072
	s_add_u32 s24, s22, 0xfffc0080
	s_addc_u32 s25, s23, -1
	s_cmp_eq_u32 s61, 12
	s_cselect_b32 s27, s5, s25
	s_cselect_b32 s26, s6, s24
	s_cselect_b32 s25, s15, s60
	s_cselect_b32 s24, s17, s59
	v_lshl_add_u64 v[210:211], s[22:23], 0, v[156:157]
	s_add_i32 m0, s36, 0xc000
	ds_read_b128 v[178:181], v177
	ds_read_b128 v[182:185], v177 offset:1024
	ds_read_b128 v[186:189], v177 offset:2048
	ds_read_b128 v[190:193], v177 offset:3072
	ds_read_b128 v[194:197], v177 offset:4096
	ds_read_b128 v[198:201], v177 offset:5120
	ds_read_b128 v[202:205], v177 offset:6144
	ds_read_b128 v[206:209], v177 offset:7168
	global_load_lds_dwordx4 v[210:211], off
	v_lshl_add_u64 v[210:211], s[22:23], 0, v[158:159]
	s_add_i32 m0, s36, 0xe000
	s_nop 0
	global_load_lds_dwordx4 v[210:211], off
	s_cmp_eq_u32 s61, -2
	s_cbranch_scc1 .Lks_p3_0
	s_waitcnt vmcnt(8)
.Lks_p3_0:
	s_waitcnt lgkmcnt(0)
	s_barrier
	s_setprio 1
	s_waitcnt lgkmcnt(0)
	v_mfma_f32_16x16x32_bf16 v[124:127], v[128:131], v[178:181], v[124:127]
	v_mfma_f32_16x16x32_bf16 v[120:123], v[136:139], v[178:181], v[120:123]
	v_mfma_f32_16x16x32_bf16 v[108:111], v[128:131], v[186:189], v[108:111]
	v_mfma_f32_16x16x32_bf16 v[104:107], v[136:139], v[186:189], v[104:107]
	v_mfma_f32_16x16x32_bf16 v[92:95], v[128:131], v[194:197], v[92:95]
	v_mfma_f32_16x16x32_bf16 v[88:91], v[136:139], v[194:197], v[88:91]
	v_mfma_f32_16x16x32_bf16 v[76:79], v[128:131], v[202:205], v[76:79]
	v_mfma_f32_16x16x32_bf16 v[72:75], v[136:139], v[202:205], v[72:75]
	v_mfma_f32_16x16x32_bf16 v[124:127], v[132:135], v[182:185], v[124:127]
	v_mfma_f32_16x16x32_bf16 v[120:123], v[140:143], v[182:185], v[120:123]
	v_mfma_f32_16x16x32_bf16 v[108:111], v[132:135], v[190:193], v[108:111]
	v_mfma_f32_16x16x32_bf16 v[104:107], v[140:143], v[190:193], v[104:107]
	v_mfma_f32_16x16x32_bf16 v[92:95], v[132:135], v[198:201], v[92:95]
	v_mfma_f32_16x16x32_bf16 v[88:91], v[140:143], v[198:201], v[88:91]
	v_mfma_f32_16x16x32_bf16 v[76:79], v[132:135], v[206:209], v[76:79]
	v_mfma_f32_16x16x32_bf16 v[72:75], v[140:143], v[206:209], v[72:75]
	s_setprio 0
	s_setprio 1
	v_mfma_f32_16x16x32_bf16 v[116:119], v[144:147], v[178:181], v[116:119]
	v_mfma_f32_16x16x32_bf16 v[112:115], v[164:167], v[178:181], v[112:115]
	v_mfma_f32_16x16x32_bf16 v[100:103], v[144:147], v[186:189], v[100:103]
	v_mfma_f32_16x16x32_bf16 v[96:99], v[164:167], v[186:189], v[96:99]
	v_mfma_f32_16x16x32_bf16 v[84:87], v[144:147], v[194:197], v[84:87]
	v_mfma_f32_16x16x32_bf16 v[80:83], v[164:167], v[194:197], v[80:83]
	v_mfma_f32_16x16x32_bf16 v[68:71], v[144:147], v[202:205], v[68:71]
	v_mfma_f32_16x16x32_bf16 v[64:67], v[164:167], v[202:205], v[64:67]
	v_mfma_f32_16x16x32_bf16 v[116:119], v[148:151], v[182:185], v[116:119]
	v_mfma_f32_16x16x32_bf16 v[112:115], v[168:171], v[182:185], v[112:115]
	v_mfma_f32_16x16x32_bf16 v[100:103], v[148:151], v[190:193], v[100:103]
	v_mfma_f32_16x16x32_bf16 v[96:99], v[168:171], v[190:193], v[96:99]
	v_mfma_f32_16x16x32_bf16 v[84:87], v[148:151], v[198:201], v[84:87]
	v_mfma_f32_16x16x32_bf16 v[80:83], v[168:171], v[198:201], v[80:83]
	v_mfma_f32_16x16x32_bf16 v[68:71], v[148:151], v[206:209], v[68:71]
	v_mfma_f32_16x16x32_bf16 v[64:67], v[168:171], v[206:209], v[64:67]
	s_setprio 0
	s_barrier
	s_add_i32 s62, s52, s34
	v_lshl_add_u64 v[210:211], s[24:25], 0, v[152:153]
	s_mov_b32 m0, s62
	ds_read_b128 v[178:181], v177 offset:16384
	ds_read_b128 v[182:185], v177 offset:17408
	ds_read_b128 v[186:189], v177 offset:18432
	ds_read_b128 v[190:193], v177 offset:19456
	ds_read_b128 v[194:197], v177 offset:20480
	ds_read_b128 v[198:201], v177 offset:21504
	ds_read_b128 v[202:205], v177 offset:22528
	ds_read_b128 v[206:209], v177 offset:23552
	global_load_lds_dwordx4 v[210:211], off
	s_add_i32 m0, s62, 0x2000
	s_add_u32 s62, s24, 0x40000
	v_lshl_add_u64 v[212:213], s[24:25], 0, v[154:155]
	s_addc_u32 s63, s25, 0
	s_add_i32 s64, s53, s34
	global_load_lds_dwordx4 v[212:213], off
	v_lshl_add_u64 v[214:215], s[62:63], 0, v[152:153]
	s_mov_b32 m0, s64
	v_lshl_add_u64 v[216:217], s[26:27], 0, v[154:155]
	global_load_lds_dwordx4 v[214:215], off
	v_lshl_add_u64 v[214:215], s[62:63], 0, v[154:155]
	s_add_i32 m0, s64, 0x2000
	s_nop 0
	global_load_lds_dwordx4 v[214:215], off
	v_lshl_add_u64 v[214:215], s[26:27], 0, v[152:153]
	s_mov_b32 m0, s36
	s_nop 0
	global_load_lds_dwordx4 v[214:215], off
	s_mov_b32 m0, s37
	s_nop 0
	global_load_lds_dwordx4 v[216:217], off
	s_cmp_eq_u32 s61, -2
	s_cbranch_scc1 .Lks_p3_1
	s_waitcnt vmcnt(8)
; #define PG8_STAGE(bufoff, gbase, voff) do { _Pragma("unroll") for (int _i = 0; _i < 2; ++_i) \
;         __builtin_amdgcn_global_load_lds((const unsigned*)((const char*)(gbase) + (voff)[_i]), (PG8_LAS unsigned*)(lds + (bufoff) + ldsw + _i * 8192), 16, 0, 0); } while (0)
; #define PG8_LDA(dst, b, h) do { _Pragma("unroll") for (int m = 0; m < 4; ++m) _Pragma("unroll") for (int k = 0; k < 2; ++k) dst[m][k] = *(const PG8_LAS bf16x8*)(lds + PG8_SA(b, h) + aoff + m * 2048 + k * 1024); } while (0)
; #define PG8_LDB(dst, b, h) do { _Pragma("unroll") for (int n = 0; n < 2; ++n) _Pragma("unroll") for (int k = 0; k < 2; ++k) dst[n][k] = *(const PG8_LAS bf16x8*)(lds + PG8_SB(b, h) + boff + n * 2048 + k * 1024); } while (0)
; #define PG8_MMA(ai, bj, At, Bt) do { __builtin_amdgcn_s_setprio(1); _Pragma("unroll") for (int m = 0; m < 4; ++m) _Pragma("unroll") for (int n = 0; n < 2; ++n) _Pragma("unroll") for (int k = 0; k < 2; ++k) \
;         acc[ai][bj][m][n] = __builtin_amdgcn_mfma_f32_16x16x32_bf16(Bt[n][k], At[m][k], acc[ai][bj][m][n], 0, 0, 0); __builtin_amdgcn_s_setprio(0); } while (0)
; #define PG8_WAIT_V(n) asm volatile("s_waitcnt vmcnt(" #n ")" ::: "memory")
; #define PG8_WAIT_L(n) asm volatile("s_waitcnt lgkmcnt(" #n ")" ::: "memory")
; #define PG8_BAR __builtin_amdgcn_s_barrier()
; #define PG8_SCHED __builtin_amdgcn_sched_barrier(0)
; template <class Epi, class Sched, bool ALIGN_EPI = false, bool SP2 = false>
; __device__ __forceinline__ void gemm_phase(PG8_LAS unsigned char* lds, const Gemm g, const Sched& S, const Epi& E) {
;     ...
;             PG8_WAIT_V(8); PG8_WAIT_L(0); PG8_BAR; PG8_MMA(1, 0, At, B0); PG8_MMA(1, 1, At, B1); PG8_BAR; PG8_SCHED;
;             PG8_LDB(B0, 1, 0); PG8_LDB(B1, 1, 1); PG8_SCHED; PG8_LDA(At, 1, 0); PG8_STAGE(PG8_SA(0, 1), a2 + hstep, voffA);
;             PG8_WAIT_V(8); PG8_WAIT_L(0); PG8_BAR; PG8_MMA(0, 0, At, B0); PG8_MMA(0, 1, At, B1); PG8_BAR; PG8_SCHED;
.Lks_p3_1:
	s_waitcnt lgkmcnt(0)
	s_barrier
	s_setprio 1
	s_waitcnt lgkmcnt(0)
	v_mfma_f32_16x16x32_bf16 v[60:63], v[128:131], v[178:181], v[60:63]
	v_mfma_f32_16x16x32_bf16 v[56:59], v[136:139], v[178:181], v[56:59]
	v_mfma_f32_16x16x32_bf16 v[44:47], v[128:131], v[186:189], v[44:47]
	v_mfma_f32_16x16x32_bf16 v[40:43], v[136:139], v[186:189], v[40:43]
	v_mfma_f32_16x16x32_bf16 v[28:31], v[128:131], v[194:197], v[28:31]
	v_mfma_f32_16x16x32_bf16 v[24:27], v[136:139], v[194:197], v[24:27]
	v_mfma_f32_16x16x32_bf16 v[12:15], v[128:131], v[202:205], v[12:15]
	v_mfma_f32_16x16x32_bf16 v[8:11], v[136:139], v[202:205], v[8:11]
	v_mfma_f32_16x16x32_bf16 v[60:63], v[132:135], v[182:185], v[60:63]
	v_mfma_f32_16x16x32_bf16 v[56:59], v[140:143], v[182:185], v[56:59]
	v_mfma_f32_16x16x32_bf16 v[44:47], v[132:135], v[190:193], v[44:47]
	v_mfma_f32_16x16x32_bf16 v[40:43], v[140:143], v[190:193], v[40:43]
	v_mfma_f32_16x16x32_bf16 v[28:31], v[132:135], v[198:201], v[28:31]
	v_mfma_f32_16x16x32_bf16 v[24:27], v[140:143], v[198:201], v[24:27]
	v_mfma_f32_16x16x32_bf16 v[12:15], v[132:135], v[206:209], v[12:15]
	v_mfma_f32_16x16x32_bf16 v[8:11], v[140:143], v[206:209], v[8:11]
	s_setprio 0
	s_setprio 1
	v_mfma_f32_16x16x32_bf16 v[52:55], v[144:147], v[178:181], v[52:55]
	v_mfma_f32_16x16x32_bf16 v[48:51], v[164:167], v[178:181], v[48:51]
	v_mfma_f32_16x16x32_bf16 v[36:39], v[144:147], v[186:189], v[36:39]
	v_mfma_f32_16x16x32_bf16 v[32:35], v[164:167], v[186:189], v[32:35]
	v_mfma_f32_16x16x32_bf16 v[20:23], v[144:147], v[194:197], v[20:23]
	v_mfma_f32_16x16x32_bf16 v[16:19], v[164:167], v[194:197], v[16:19]
	v_mfma_f32_16x16x32_bf16 v[4:7], v[144:147], v[202:205], v[4:7]
	v_mfma_f32_16x16x32_bf16 v[0:3], v[164:167], v[202:205], v[0:3]
	v_mfma_f32_16x16x32_bf16 v[52:55], v[148:151], v[182:185], v[52:55]
	v_mfma_f32_16x16x32_bf16 v[48:51], v[168:171], v[182:185], v[48:51]
	v_mfma_f32_16x16x32_bf16 v[36:39], v[148:151], v[190:193], v[36:39]
	v_mfma_f32_16x16x32_bf16 v[32:35], v[168:171], v[190:193], v[32:35]
	v_mfma_f32_16x16x32_bf16 v[20:23], v[148:151], v[198:201], v[20:23]
	v_mfma_f32_16x16x32_bf16 v[16:19], v[168:171], v[198:201], v[16:19]
	v_mfma_f32_16x16x32_bf16 v[4:7], v[148:151], v[206:209], v[4:7]
	v_mfma_f32_16x16x32_bf16 v[0:3], v[168:171], v[206:209], v[0:3]
	s_setprio 0
	s_barrier
	s_add_i32 s62, 0, 0x18000
	s_add_i32 s63, 0, 0x1c000
	v_add_u32_e32 v140, s62, v174
	v_add_u32_e32 v168, s63, v174
	ds_read_b128 v[128:131], v140
	ds_read_b128 v[132:135], v140 offset:1024
	ds_read_b128 v[136:139], v140 offset:2048
	ds_read_b128 v[140:143], v140 offset:3072
	ds_read_b128 v[144:147], v168
	ds_read_b128 v[148:151], v168 offset:1024
	ds_read_b128 v[164:167], v168 offset:2048
	ds_read_b128 v[168:171], v168 offset:3072
	s_add_u32 s26, s26, 0x40000
	s_addc_u32 s27, s27, 0
	s_mov_b32 m0, s38
	v_lshl_add_u64 v[218:219], s[26:27], 0, v[152:153]
	ds_read_b128 v[178:181], v177 offset:32768
	ds_read_b128 v[182:185], v177 offset:33792
	ds_read_b128 v[186:189], v177 offset:34816
	ds_read_b128 v[190:193], v177 offset:35840
	ds_read_b128 v[194:197], v177 offset:36864
	ds_read_b128 v[198:201], v177 offset:37888
	ds_read_b128 v[202:205], v177 offset:38912
	ds_read_b128 v[206:209], v177 offset:39936
	global_load_lds_dwordx4 v[218:219], off
	v_lshl_add_u64 v[218:219], s[26:27], 0, v[154:155]
	s_mov_b32 m0, s39
	s_nop 0
	global_load_lds_dwordx4 v[218:219], off
	s_waitcnt vmcnt(8)
	s_waitcnt lgkmcnt(0)
	s_barrier
	s_setprio 1
	s_waitcnt lgkmcnt(0)
	v_mfma_f32_16x16x32_bf16 v[124:127], v[128:131], v[178:181], v[124:127]
	v_mfma_f32_16x16x32_bf16 v[120:123], v[136:139], v[178:181], v[120:123]
	v_mfma_f32_16x16x32_bf16 v[108:111], v[128:131], v[186:189], v[108:111]
	v_mfma_f32_16x16x32_bf16 v[104:107], v[136:139], v[186:189], v[104:107]
	v_mfma_f32_16x16x32_bf16 v[92:95], v[128:131], v[194:197], v[92:95]
	v_mfma_f32_16x16x32_bf16 v[88:91], v[136:139], v[194:197], v[88:91]
	v_mfma_f32_16x16x32_bf16 v[76:79], v[128:131], v[202:205], v[76:79]
	v_mfma_f32_16x16x32_bf16 v[72:75], v[136:139], v[202:205], v[72:75]
	v_mfma_f32_16x16x32_bf16 v[124:127], v[132:135], v[182:185], v[124:127]
	v_mfma_f32_16x16x32_bf16 v[120:123], v[140:143], v[182:185], v[120:123]
	v_mfma_f32_16x16x32_bf16 v[108:111], v[132:135], v[190:193], v[108:111]
	v_mfma_f32_16x16x32_bf16 v[104:107], v[140:143], v[190:193], v[104:107]
	v_mfma_f32_16x16x32_bf16 v[92:95], v[132:135], v[198:201], v[92:95]
	v_mfma_f32_16x16x32_bf16 v[88:91], v[140:143], v[198:201], v[88:91]
	v_mfma_f32_16x16x32_bf16 v[76:79], v[132:135], v[206:209], v[76:79]
	v_mfma_f32_16x16x32_bf16 v[72:75], v[140:143], v[206:209], v[72:75]
	s_setprio 0
	s_setprio 1
	v_mfma_f32_16x16x32_bf16 v[116:119], v[144:147], v[178:181], v[116:119]
	v_mfma_f32_16x16x32_bf16 v[112:115], v[164:167], v[178:181], v[112:115]
	v_mfma_f32_16x16x32_bf16 v[100:103], v[144:147], v[186:189], v[100:103]
	v_mfma_f32_16x16x32_bf16 v[96:99], v[164:167], v[186:189], v[96:99]
	v_mfma_f32_16x16x32_bf16 v[84:87], v[144:147], v[194:197], v[84:87]
	v_mfma_f32_16x16x32_bf16 v[80:83], v[164:167], v[194:197], v[80:83]
	v_mfma_f32_16x16x32_bf16 v[68:71], v[144:147], v[202:205], v[68:71]
	v_mfma_f32_16x16x32_bf16 v[64:67], v[164:167], v[202:205], v[64:67]
	v_mfma_f32_16x16x32_bf16 v[116:119], v[148:151], v[182:185], v[116:119]
	v_mfma_f32_16x16x32_bf16 v[112:115], v[168:171], v[182:185], v[112:115]
	v_mfma_f32_16x16x32_bf16 v[100:103], v[148:151], v[190:193], v[100:103]
	v_mfma_f32_16x16x32_bf16 v[96:99], v[168:171], v[190:193], v[96:99]
	v_mfma_f32_16x16x32_bf16 v[84:87], v[148:151], v[198:201], v[84:87]
	v_mfma_f32_16x16x32_bf16 v[80:83], v[168:171], v[198:201], v[80:83]
	v_mfma_f32_16x16x32_bf16 v[68:71], v[148:151], v[206:209], v[68:71]
	v_mfma_f32_16x16x32_bf16 v[64:67], v[168:171], v[206:209], v[64:67]
	s_setprio 0
	s_barrier
; #define PG8_STAGE(bufoff, gbase, voff) do { _Pragma("unroll") for (int _i = 0; _i < 2; ++_i) \
;         __builtin_amdgcn_global_load_lds((const unsigned*)((const char*)(gbase) + (voff)[_i]), (PG8_LAS unsigned*)(lds + (bufoff) + ldsw + _i * 8192), 16, 0, 0); } while (0)
; #define PG8_LDA(dst, b, h) do { _Pragma("unroll") for (int m = 0; m < 4; ++m) _Pragma("unroll") for (int k = 0; k < 2; ++k) dst[m][k] = *(const PG8_LAS bf16x8*)(lds + PG8_SA(b, h) + aoff + m * 2048 + k * 1024); } while (0)
; #define PG8_MMA(ai, bj, At, Bt) do { __builtin_amdgcn_s_setprio(1); _Pragma("unroll") for (int m = 0; m < 4; ++m) _Pragma("unroll") for (int n = 0; n < 2; ++n) _Pragma("unroll") for (int k = 0; k < 2; ++k) \
;         acc[ai][bj][m][n] = __builtin_amdgcn_mfma_f32_16x16x32_bf16(Bt[n][k], At[m][k], acc[ai][bj][m][n], 0, 0, 0); __builtin_amdgcn_s_setprio(0); } while (0)
; #define PG8_WAIT_V(n) asm volatile("s_waitcnt vmcnt(" #n ")" ::: "memory")
; #define PG8_WAIT_L(n) asm volatile("s_waitcnt lgkmcnt(" #n ")" ::: "memory")
; #define PG8_BAR __builtin_amdgcn_s_barrier()
; #define PG8_SCHED __builtin_amdgcn_sched_barrier(0)
; template <class Epi, class Sched, bool ALIGN_EPI = false, bool SP2 = false>
; __device__ __forceinline__ void gemm_phase(PG8_LAS unsigned char* lds, const Gemm g, const Sched& S, const Epi& E) {
;     ...
;         for (int t = 0; t < nt; t += 2) {
;     ...
;             PG8_LDA(At, 1, 1); PG8_STAGE(PG8_SB(1, 0), b3, voffB); PG8_STAGE(PG8_SB(1, 1), b3 + hstep, voffB); PG8_STAGE(PG8_SA(1, 0), a3, voffA);
;             PG8_WAIT_V(8); PG8_WAIT_L(0); PG8_BAR; PG8_MMA(1, 0, At, B0); PG8_MMA(1, 1, At, B1); PG8_BAR; PG8_SCHED;
	s_add_i32 s26, s62, s34
	v_lshl_add_u64 v[210:211], v[210:211], 0, s[10:11]
	s_mov_b32 m0, s26
	ds_read_b128 v[178:181], v177 offset:49152
	ds_read_b128 v[182:185], v177 offset:50176
	ds_read_b128 v[186:189], v177 offset:51200
	ds_read_b128 v[190:193], v177 offset:52224
	ds_read_b128 v[194:197], v177 offset:53248
	ds_read_b128 v[198:201], v177 offset:54272
	ds_read_b128 v[202:205], v177 offset:55296
	ds_read_b128 v[206:209], v177 offset:56320
	global_load_lds_dwordx4 v[210:211], off
	s_add_i32 m0, s26, 0x2000
	s_add_u32 s24, s24, 0x40080
	v_lshl_add_u64 v[210:211], v[212:213], 0, s[10:11]
	s_addc_u32 s25, s25, 0
	s_add_i32 s26, s63, s34
	global_load_lds_dwordx4 v[210:211], off
	v_lshl_add_u64 v[210:211], s[24:25], 0, v[152:153]
	s_mov_b32 m0, s26
	s_nop 0
	global_load_lds_dwordx4 v[210:211], off
	v_lshl_add_u64 v[210:211], s[24:25], 0, v[154:155]
	s_add_i32 m0, s26, 0x2000
	s_nop 0
	global_load_lds_dwordx4 v[210:211], off
	v_lshl_add_u64 v[210:211], v[214:215], 0, s[10:11]
	s_mov_b32 m0, s45
	s_nop 0
	global_load_lds_dwordx4 v[210:211], off
	v_lshl_add_u64 v[210:211], v[216:217], 0, s[10:11]
	s_mov_b32 m0, s46
	s_nop 0
	global_load_lds_dwordx4 v[210:211], off
	s_waitcnt vmcnt(8)
	s_waitcnt lgkmcnt(0)
	s_barrier
	s_setprio 1
	s_waitcnt lgkmcnt(0)
	v_mfma_f32_16x16x32_bf16 v[60:63], v[128:131], v[178:181], v[60:63]
	v_mfma_f32_16x16x32_bf16 v[56:59], v[136:139], v[178:181], v[56:59]
	v_mfma_f32_16x16x32_bf16 v[44:47], v[128:131], v[186:189], v[44:47]
	v_mfma_f32_16x16x32_bf16 v[40:43], v[136:139], v[186:189], v[40:43]
	v_mfma_f32_16x16x32_bf16 v[28:31], v[128:131], v[194:197], v[28:31]
	v_mfma_f32_16x16x32_bf16 v[24:27], v[136:139], v[194:197], v[24:27]
	v_mfma_f32_16x16x32_bf16 v[12:15], v[128:131], v[202:205], v[12:15]
	v_mfma_f32_16x16x32_bf16 v[8:11], v[136:139], v[202:205], v[8:11]
	v_mfma_f32_16x16x32_bf16 v[60:63], v[132:135], v[182:185], v[60:63]
	v_mfma_f32_16x16x32_bf16 v[56:59], v[140:143], v[182:185], v[56:59]
	v_mfma_f32_16x16x32_bf16 v[44:47], v[132:135], v[190:193], v[44:47]
	v_mfma_f32_16x16x32_bf16 v[40:43], v[140:143], v[190:193], v[40:43]
	v_mfma_f32_16x16x32_bf16 v[28:31], v[132:135], v[198:201], v[28:31]
	v_mfma_f32_16x16x32_bf16 v[24:27], v[140:143], v[198:201], v[24:27]
	v_mfma_f32_16x16x32_bf16 v[12:15], v[132:135], v[206:209], v[12:15]
	v_mfma_f32_16x16x32_bf16 v[8:11], v[140:143], v[206:209], v[8:11]
	s_setprio 0
	s_setprio 1
	v_mfma_f32_16x16x32_bf16 v[52:55], v[144:147], v[178:181], v[52:55]
	v_mfma_f32_16x16x32_bf16 v[48:51], v[164:167], v[178:181], v[48:51]
	v_mfma_f32_16x16x32_bf16 v[36:39], v[144:147], v[186:189], v[36:39]
	v_mfma_f32_16x16x32_bf16 v[32:35], v[164:167], v[186:189], v[32:35]
	v_mfma_f32_16x16x32_bf16 v[20:23], v[144:147], v[194:197], v[20:23]
	v_mfma_f32_16x16x32_bf16 v[16:19], v[164:167], v[194:197], v[16:19]
	v_mfma_f32_16x16x32_bf16 v[4:7], v[144:147], v[202:205], v[4:7]
	v_mfma_f32_16x16x32_bf16 v[0:3], v[164:167], v[202:205], v[0:3]
	v_mfma_f32_16x16x32_bf16 v[52:55], v[148:151], v[182:185], v[52:55]
	v_mfma_f32_16x16x32_bf16 v[48:51], v[168:171], v[182:185], v[48:51]
	v_mfma_f32_16x16x32_bf16 v[36:39], v[148:151], v[190:193], v[36:39]
	v_mfma_f32_16x16x32_bf16 v[32:35], v[168:171], v[190:193], v[32:35]
	v_mfma_f32_16x16x32_bf16 v[20:23], v[148:151], v[198:201], v[20:23]
	v_mfma_f32_16x16x32_bf16 v[16:19], v[168:171], v[198:201], v[16:19]
	v_mfma_f32_16x16x32_bf16 v[4:7], v[148:151], v[206:209], v[4:7]
	v_mfma_f32_16x16x32_bf16 v[0:3], v[168:171], v[206:209], v[0:3]
	s_setprio 0
	s_barrier
	s_add_i32 s61, s61, 2
	s_add_u32 s22, s22, 0x100
	s_addc_u32 s23, s23, 0
	s_add_u32 s59, s59, 0x100
	s_addc_u32 s60, s60, 0
	s_cmp_gt_u32 s61, 13
	s_cbranch_scc0 .LBB0_1236
	s_and_b64 vcc, exec, s[12:13]
	s_cbranch_vccz .LBB0_1239
	s_barrier
